# grid barrier release: waiting workgroups poll the top-level generation word directly (one polling hop less); on top of hgrn_scan hoist + P9 hand loop/tile + head-major QKV
# speedup vs baseline: 1.0028x; 1.0028x over previous
; __device__ __forceinline__ unsigned xb_ld(unsigned* p)              { return __hip_atomic_load(p, __ATOMIC_RELAXED, __HIP_MEMORY_SCOPE_AGENT); }
; __device__ __forceinline__ unsigned xb_add(unsigned* p, unsigned v) { return __hip_atomic_fetch_add(p, v, __ATOMIC_RELAXED, __HIP_MEMORY_SCOPE_AGENT); }
; #define XB_SPIN(cond, bar) do { unsigned _sp = 0; while (cond) { __builtin_amdgcn_s_sleep(1); \
;     if ((++_sp & 255u) == 0u) { if (xb_ld(&(bar)[XB_TMO])) break; if (_sp > XB_SPIN_CAP) { atomicAdd(&(bar)[XB_TMO], 1u); break; } } } } while (0)
; __device__ __forceinline__ void xcd_barrier(const XcdBarrier& b) {
;     ...
;         const unsigned old = xb_add(&bar[XB_XSUB(b.x)], 1u);
;         const unsigned gen = old / nloc;
;         if (old + 1u == (gen + 1u) * nloc) {
;             __builtin_amdgcn_fence(__ATOMIC_RELEASE, "agent");
;             asm volatile("s_waitcnt vmcnt(0)" ::: "memory");
;             const unsigned og = xb_add(&bar[XB_TOP], 1u);
;             const unsigned tg = og / nx;
;             if (og + 1u == (tg + 1u) * nx) xb_add(&bar[XB_TOPGEN], 1u);
;             else XB_SPIN(xb_ld(&bar[XB_TOPGEN]) == tg, bar);
;             __builtin_amdgcn_fence(__ATOMIC_ACQUIRE, "agent");
;             xb_add(&bar[XB_XGEN(b.x)], 1u);
;             asm volatile("s_waitcnt vmcnt(0)" ::: "memory");
;         } else {
;             XB_SPIN(xb_ld(&bar[XB_XGEN(b.x)]) == gen, bar);
.LBB0_57:
	s_or_b64 exec, exec, s[12:13]
	v_cvt_f32_u32_e32 v5, v3
	s_waitcnt vmcnt(0)
	v_readfirstlane_b32 s0, v4
	v_sub_u32_e32 v4, 0, v3
	v_rcp_iflag_f32_e32 v5, v5
	v_add_u32_e32 v6, s0, v2
	v_mul_f32_e32 v5, 0x4f7ffffe, v5
	v_cvt_u32_f32_e32 v5, v5
	v_mul_lo_u32 v2, v4, v5
	v_mul_hi_u32 v2, v5, v2
	v_add_u32_e32 v2, v5, v2
	v_mul_hi_u32 v2, v6, v2
	v_mul_lo_u32 v4, v2, v3
	v_sub_u32_e32 v4, v6, v4
	v_add_u32_e32 v5, 1, v2
	v_cmp_ge_u32_e32 vcc, v4, v3
	s_nop 1
	v_cndmask_b32_e32 v2, v2, v5, vcc
	v_sub_u32_e32 v5, v4, v3
	v_cndmask_b32_e32 v4, v4, v5, vcc
	v_add_u32_e32 v5, 1, v2
	v_cmp_ge_u32_e32 vcc, v4, v3
	v_add_u32_e32 v4, 1, v6
	s_nop 0
	v_cndmask_b32_e32 v2, v2, v5, vcc
	v_mul_lo_u32 v5, v3, v2
	v_add_u32_e32 v3, v5, v3
	v_cmp_ne_u32_e32 vcc, v4, v3
	s_and_saveexec_b64 s[0:1], vcc
	s_xor_b64 s[10:11], exec, s[0:1]
	s_cbranch_execz .LBB0_71
	s_waitcnt lgkmcnt(0)
	v_mov_b32_e32 v1, 0x7100
	global_load_dword v1, v1, s[30:31] offset:1024 sc1
	s_add_u32 s16, s30, 0x7500
	s_addc_u32 s17, s31, 0
	s_waitcnt vmcnt(0)
	v_cmp_eq_u32_e32 vcc, v1, v2
	s_and_saveexec_b64 s[12:13], vcc
	s_cbranch_execz .LBB0_70
	s_add_u32 s14, s30, 0x4200
	s_addc_u32 s15, s31, 0
	s_mov_b32 s0, 1
	s_mov_b64 s[18:19], 0
	v_mov_b32_e32 v1, 0
	s_branch .LBB0_61

; __device__ __forceinline__ unsigned xb_ld(unsigned* p)              { return __hip_atomic_load(p, __ATOMIC_RELAXED, __HIP_MEMORY_SCOPE_AGENT); }
; __device__ __forceinline__ unsigned xb_add(unsigned* p, unsigned v) { return __hip_atomic_fetch_add(p, v, __ATOMIC_RELAXED, __HIP_MEMORY_SCOPE_AGENT); }
; #define XB_SPIN(cond, bar) do { unsigned _sp = 0; while (cond) { __builtin_amdgcn_s_sleep(1); \
;     if ((++_sp & 255u) == 0u) { if (xb_ld(&(bar)[XB_TMO])) break; if (_sp > XB_SPIN_CAP) { atomicAdd(&(bar)[XB_TMO], 1u); break; } } } } while (0)
; __device__ __forceinline__ void xcd_barrier(const XcdBarrier& b) {
;     ...
;         const unsigned old = xb_add(&bar[XB_XSUB(b.x)], 1u);
;         const unsigned gen = old / nloc;
;         if (old + 1u == (gen + 1u) * nloc) {
;             __builtin_amdgcn_fence(__ATOMIC_RELEASE, "agent");
;             asm volatile("s_waitcnt vmcnt(0)" ::: "memory");
;             const unsigned og = xb_add(&bar[XB_TOP], 1u);
;             const unsigned tg = og / nx;
;             if (og + 1u == (tg + 1u) * nx) xb_add(&bar[XB_TOPGEN], 1u);
;             else XB_SPIN(xb_ld(&bar[XB_TOPGEN]) == tg, bar);
;             __builtin_amdgcn_fence(__ATOMIC_ACQUIRE, "agent");
;             xb_add(&bar[XB_XGEN(b.x)], 1u);
;             asm volatile("s_waitcnt vmcnt(0)" ::: "memory");
;         } else {
;             XB_SPIN(xb_ld(&bar[XB_XGEN(b.x)]) == gen, bar);
.LBB0_607:
	s_or_b64 exec, exec, s[12:13]
	v_cvt_f32_u32_e32 v6, v4
	s_waitcnt vmcnt(0)
	v_readfirstlane_b32 s0, v5
	v_sub_u32_e32 v5, 0, v4
	v_rcp_iflag_f32_e32 v6, v6
	v_add_u32_e32 v7, s0, v3
	v_mul_f32_e32 v6, 0x4f7ffffe, v6
	v_cvt_u32_f32_e32 v6, v6
	v_mul_lo_u32 v3, v5, v6
	v_mul_hi_u32 v3, v6, v3
	v_add_u32_e32 v3, v6, v3
	v_mul_hi_u32 v3, v7, v3
	v_mul_lo_u32 v5, v3, v4
	v_sub_u32_e32 v5, v7, v5
	v_add_u32_e32 v6, 1, v3
	v_cmp_ge_u32_e32 vcc, v5, v4
	s_nop 1
	v_cndmask_b32_e32 v3, v3, v6, vcc
	v_sub_u32_e32 v6, v5, v4
	v_cndmask_b32_e32 v5, v5, v6, vcc
	v_add_u32_e32 v6, 1, v3
	v_cmp_ge_u32_e32 vcc, v5, v4
	v_add_u32_e32 v5, 1, v7
	s_nop 0
	v_cndmask_b32_e32 v3, v3, v6, vcc
	v_mul_lo_u32 v6, v4, v3
	v_add_u32_e32 v4, v6, v4
	v_cmp_ne_u32_e32 vcc, v5, v4
	s_and_saveexec_b64 s[0:1], vcc
	s_xor_b64 s[10:11], exec, s[0:1]
	s_cbranch_execz .LBB0_621
	s_waitcnt lgkmcnt(0)
	v_mov_b32_e32 v2, 0x7100
	global_load_dword v2, v2, s[30:31] offset:1024 sc1
	s_add_u32 s16, s30, 0x7500
	s_addc_u32 s17, s31, 0
	s_waitcnt vmcnt(0)
	v_cmp_eq_u32_e32 vcc, v2, v3
	s_and_saveexec_b64 s[12:13], vcc
	s_cbranch_execz .LBB0_620
	s_add_u32 s14, s30, 0x4200
	s_addc_u32 s15, s31, 0
	s_mov_b32 s0, 1
	s_mov_b64 s[18:19], 0
	v_mov_b32_e32 v2, 0
	s_branch .LBB0_611

; __device__ __forceinline__ unsigned xb_ld(unsigned* p)              { return __hip_atomic_load(p, __ATOMIC_RELAXED, __HIP_MEMORY_SCOPE_AGENT); }
; __device__ __forceinline__ unsigned xb_add(unsigned* p, unsigned v) { return __hip_atomic_fetch_add(p, v, __ATOMIC_RELAXED, __HIP_MEMORY_SCOPE_AGENT); }
; #define XB_SPIN(cond, bar) do { unsigned _sp = 0; while (cond) { __builtin_amdgcn_s_sleep(1); \
;     if ((++_sp & 255u) == 0u) { if (xb_ld(&(bar)[XB_TMO])) break; if (_sp > XB_SPIN_CAP) { atomicAdd(&(bar)[XB_TMO], 1u); break; } } } } while (0)
; __device__ __forceinline__ void xcd_barrier(const XcdBarrier& b) {
;     ...
;         const unsigned old = xb_add(&bar[XB_XSUB(b.x)], 1u);
;         const unsigned gen = old / nloc;
;         if (old + 1u == (gen + 1u) * nloc) {
;             __builtin_amdgcn_fence(__ATOMIC_RELEASE, "agent");
;             asm volatile("s_waitcnt vmcnt(0)" ::: "memory");
;             const unsigned og = xb_add(&bar[XB_TOP], 1u);
;             const unsigned tg = og / nx;
;             if (og + 1u == (tg + 1u) * nx) xb_add(&bar[XB_TOPGEN], 1u);
;             else XB_SPIN(xb_ld(&bar[XB_TOPGEN]) == tg, bar);
;             __builtin_amdgcn_fence(__ATOMIC_ACQUIRE, "agent");
;             xb_add(&bar[XB_XGEN(b.x)], 1u);
;             asm volatile("s_waitcnt vmcnt(0)" ::: "memory");
;         } else {
;             XB_SPIN(xb_ld(&bar[XB_XGEN(b.x)]) == gen, bar);
.LBB0_784:
	s_or_b64 exec, exec, s[14:15]
	v_cvt_f32_u32_e32 v6, v4
	s_waitcnt vmcnt(0)
	v_readfirstlane_b32 s0, v5
	v_sub_u32_e32 v5, 0, v4
	v_rcp_iflag_f32_e32 v6, v6
	v_add_u32_e32 v7, s0, v3
	v_mul_f32_e32 v6, 0x4f7ffffe, v6
	v_cvt_u32_f32_e32 v6, v6
	v_mul_lo_u32 v3, v5, v6
	v_mul_hi_u32 v3, v6, v3
	v_add_u32_e32 v3, v6, v3
	v_mul_hi_u32 v3, v7, v3
	v_mul_lo_u32 v5, v3, v4
	v_sub_u32_e32 v5, v7, v5
	v_add_u32_e32 v6, 1, v3
	v_cmp_ge_u32_e32 vcc, v5, v4
	s_nop 1
	v_cndmask_b32_e32 v3, v3, v6, vcc
	v_sub_u32_e32 v6, v5, v4
	v_cndmask_b32_e32 v5, v5, v6, vcc
	v_add_u32_e32 v6, 1, v3
	v_cmp_ge_u32_e32 vcc, v5, v4
	v_add_u32_e32 v5, 1, v7
	s_nop 0
	v_cndmask_b32_e32 v3, v3, v6, vcc
	v_mul_lo_u32 v6, v4, v3
	v_add_u32_e32 v4, v6, v4
	v_cmp_ne_u32_e32 vcc, v5, v4
	s_and_saveexec_b64 s[0:1], vcc
	s_xor_b64 s[12:13], exec, s[0:1]
	s_cbranch_execz .LBB0_798
	s_waitcnt lgkmcnt(0)
	v_mov_b32_e32 v2, 0x7100
	global_load_dword v2, v2, s[30:31] offset:1024 sc1
	s_add_u32 s18, s30, 0x7500
	s_addc_u32 s19, s31, 0
	s_waitcnt vmcnt(0)
	v_cmp_eq_u32_e32 vcc, v2, v3
	s_and_saveexec_b64 s[14:15], vcc
	s_cbranch_execz .LBB0_797
	s_add_u32 s16, s30, 0x4200
	s_addc_u32 s17, s31, 0
	s_mov_b32 s0, 1
	s_mov_b64 s[20:21], 0
	v_mov_b32_e32 v2, 0
	s_branch .LBB0_788

; __device__ __forceinline__ unsigned xb_ld(unsigned* p)              { return __hip_atomic_load(p, __ATOMIC_RELAXED, __HIP_MEMORY_SCOPE_AGENT); }
; __device__ __forceinline__ unsigned xb_add(unsigned* p, unsigned v) { return __hip_atomic_fetch_add(p, v, __ATOMIC_RELAXED, __HIP_MEMORY_SCOPE_AGENT); }
; #define XB_SPIN(cond, bar) do { unsigned _sp = 0; while (cond) { __builtin_amdgcn_s_sleep(1); \
;     if ((++_sp & 255u) == 0u) { if (xb_ld(&(bar)[XB_TMO])) break; if (_sp > XB_SPIN_CAP) { atomicAdd(&(bar)[XB_TMO], 1u); break; } } } } while (0)
; __device__ __forceinline__ void xcd_barrier(const XcdBarrier& b) {
;     ...
;         const unsigned old = xb_add(&bar[XB_XSUB(b.x)], 1u);
;         const unsigned gen = old / nloc;
;         if (old + 1u == (gen + 1u) * nloc) {
;             __builtin_amdgcn_fence(__ATOMIC_RELEASE, "agent");
;             asm volatile("s_waitcnt vmcnt(0)" ::: "memory");
;             const unsigned og = xb_add(&bar[XB_TOP], 1u);
;             const unsigned tg = og / nx;
;             if (og + 1u == (tg + 1u) * nx) xb_add(&bar[XB_TOPGEN], 1u);
;             else XB_SPIN(xb_ld(&bar[XB_TOPGEN]) == tg, bar);
;             __builtin_amdgcn_fence(__ATOMIC_ACQUIRE, "agent");
;             xb_add(&bar[XB_XGEN(b.x)], 1u);
;             asm volatile("s_waitcnt vmcnt(0)" ::: "memory");
;         } else {
;             XB_SPIN(xb_ld(&bar[XB_XGEN(b.x)]) == gen, bar);
.LBB0_1589:
	s_or_b64 exec, exec, s[10:11]
	v_cvt_f32_u32_e32 v6, v4
	s_waitcnt vmcnt(0)
	v_readfirstlane_b32 s3, v5
	v_sub_u32_e32 v5, 0, v4
	v_rcp_iflag_f32_e32 v6, v6
	v_add_u32_e32 v7, s3, v3
	v_mul_f32_e32 v6, 0x4f7ffffe, v6
	v_cvt_u32_f32_e32 v6, v6
	v_mul_lo_u32 v3, v5, v6
	v_mul_hi_u32 v3, v6, v3
	v_add_u32_e32 v3, v6, v3
	v_mul_hi_u32 v3, v7, v3
	v_mul_lo_u32 v5, v3, v4
	v_sub_u32_e32 v5, v7, v5
	v_add_u32_e32 v6, 1, v3
	v_cmp_ge_u32_e32 vcc, v5, v4
	s_nop 1
	v_cndmask_b32_e32 v3, v3, v6, vcc
	v_sub_u32_e32 v6, v5, v4
	v_cndmask_b32_e32 v5, v5, v6, vcc
	v_add_u32_e32 v6, 1, v3
	v_cmp_ge_u32_e32 vcc, v5, v4
	v_add_u32_e32 v5, 1, v7
	s_nop 0
	v_cndmask_b32_e32 v3, v3, v6, vcc
	v_mul_lo_u32 v6, v4, v3
	v_add_u32_e32 v4, v6, v4
	v_cmp_ne_u32_e32 vcc, v5, v4
	s_and_saveexec_b64 s[8:9], vcc
	s_xor_b64 s[8:9], exec, s[8:9]
	s_cbranch_execz .LBB0_1603
	s_waitcnt lgkmcnt(0)
	v_mov_b32_e32 v2, 0x7100
	global_load_dword v2, v2, s[30:31] offset:1024 sc1
	s_add_u32 s14, s30, 0x7500
	s_addc_u32 s15, s31, 0
	s_waitcnt vmcnt(0)
	v_cmp_eq_u32_e32 vcc, v2, v3
	s_and_saveexec_b64 s[10:11], vcc
	s_cbranch_execz .LBB0_1602
	s_add_u32 s12, s30, 0x4200
	s_addc_u32 s13, s31, 0
	s_mov_b32 s3, 1
	s_mov_b64 s[16:17], 0
	v_mov_b32_e32 v2, 0
	s_branch .LBB0_1593

; __device__ __forceinline__ unsigned xb_ld(unsigned* p)              { return __hip_atomic_load(p, __ATOMIC_RELAXED, __HIP_MEMORY_SCOPE_AGENT); }
; __device__ __forceinline__ unsigned xb_add(unsigned* p, unsigned v) { return __hip_atomic_fetch_add(p, v, __ATOMIC_RELAXED, __HIP_MEMORY_SCOPE_AGENT); }
; #define XB_SPIN(cond, bar) do { unsigned _sp = 0; while (cond) { __builtin_amdgcn_s_sleep(1); \
;     if ((++_sp & 255u) == 0u) { if (xb_ld(&(bar)[XB_TMO])) break; if (_sp > XB_SPIN_CAP) { atomicAdd(&(bar)[XB_TMO], 1u); break; } } } } while (0)
; __device__ __forceinline__ void xcd_barrier(const XcdBarrier& b) {
;     ...
;         const unsigned old = xb_add(&bar[XB_XSUB(b.x)], 1u);
;         const unsigned gen = old / nloc;
;         if (old + 1u == (gen + 1u) * nloc) {
;             __builtin_amdgcn_fence(__ATOMIC_RELEASE, "agent");
;             asm volatile("s_waitcnt vmcnt(0)" ::: "memory");
;             const unsigned og = xb_add(&bar[XB_TOP], 1u);
;             const unsigned tg = og / nx;
;             if (og + 1u == (tg + 1u) * nx) xb_add(&bar[XB_TOPGEN], 1u);
;             else XB_SPIN(xb_ld(&bar[XB_TOPGEN]) == tg, bar);
;             __builtin_amdgcn_fence(__ATOMIC_ACQUIRE, "agent");
;             xb_add(&bar[XB_XGEN(b.x)], 1u);
;             asm volatile("s_waitcnt vmcnt(0)" ::: "memory");
;         } else {
;             XB_SPIN(xb_ld(&bar[XB_XGEN(b.x)]) == gen, bar);
.LBB0_2040:
	s_or_b64 exec, exec, s[10:11]
	v_cvt_f32_u32_e32 v5, v3
	s_waitcnt vmcnt(0)
	v_readfirstlane_b32 s3, v4
	v_sub_u32_e32 v4, 0, v3
	v_rcp_iflag_f32_e32 v5, v5
	v_add_u32_e32 v6, s3, v2
	v_mul_f32_e32 v5, 0x4f7ffffe, v5
	v_cvt_u32_f32_e32 v5, v5
	v_mul_lo_u32 v2, v4, v5
	v_mul_hi_u32 v2, v5, v2
	v_add_u32_e32 v2, v5, v2
	v_mul_hi_u32 v2, v6, v2
	v_mul_lo_u32 v4, v2, v3
	v_sub_u32_e32 v4, v6, v4
	v_add_u32_e32 v5, 1, v2
	v_cmp_ge_u32_e32 vcc, v4, v3
	s_nop 1
	v_cndmask_b32_e32 v2, v2, v5, vcc
	v_sub_u32_e32 v5, v4, v3
	v_cndmask_b32_e32 v4, v4, v5, vcc
	v_add_u32_e32 v5, 1, v2
	v_cmp_ge_u32_e32 vcc, v4, v3
	v_add_u32_e32 v4, 1, v6
	s_nop 0
	v_cndmask_b32_e32 v2, v2, v5, vcc
	v_mul_lo_u32 v5, v3, v2
	v_add_u32_e32 v3, v5, v3
	v_cmp_ne_u32_e32 vcc, v4, v3
	s_and_saveexec_b64 s[8:9], vcc
	s_xor_b64 s[8:9], exec, s[8:9]
	s_cbranch_execz .LBB0_2054
	s_waitcnt lgkmcnt(0)
	v_mov_b32_e32 v1, 0x7100
	global_load_dword v1, v1, s[30:31] offset:1024 sc1
	s_add_u32 s14, s30, 0x7500
	s_addc_u32 s15, s31, 0
	s_waitcnt vmcnt(0)
	v_cmp_eq_u32_e32 vcc, v1, v2
	s_and_saveexec_b64 s[10:11], vcc
	s_cbranch_execz .LBB0_2053
	s_add_u32 s12, s30, 0x4200
	s_addc_u32 s13, s31, 0
	s_mov_b32 s3, 1
	s_mov_b64 s[16:17], 0
	v_mov_b32_e32 v1, 0
	s_branch .LBB0_2044

; __device__ __forceinline__ unsigned xb_ld(unsigned* p)              { return __hip_atomic_load(p, __ATOMIC_RELAXED, __HIP_MEMORY_SCOPE_AGENT); }
; __device__ __forceinline__ unsigned xb_add(unsigned* p, unsigned v) { return __hip_atomic_fetch_add(p, v, __ATOMIC_RELAXED, __HIP_MEMORY_SCOPE_AGENT); }
; #define XB_SPIN(cond, bar) do { unsigned _sp = 0; while (cond) { __builtin_amdgcn_s_sleep(1); \
;     if ((++_sp & 255u) == 0u) { if (xb_ld(&(bar)[XB_TMO])) break; if (_sp > XB_SPIN_CAP) { atomicAdd(&(bar)[XB_TMO], 1u); break; } } } } while (0)
; __device__ __forceinline__ void xcd_barrier(const XcdBarrier& b) {
;     ...
;         const unsigned old = xb_add(&bar[XB_XSUB(b.x)], 1u);
;         const unsigned gen = old / nloc;
;         if (old + 1u == (gen + 1u) * nloc) {
;             __builtin_amdgcn_fence(__ATOMIC_RELEASE, "agent");
;             asm volatile("s_waitcnt vmcnt(0)" ::: "memory");
;             const unsigned og = xb_add(&bar[XB_TOP], 1u);
;             const unsigned tg = og / nx;
;             if (og + 1u == (tg + 1u) * nx) xb_add(&bar[XB_TOPGEN], 1u);
;             else XB_SPIN(xb_ld(&bar[XB_TOPGEN]) == tg, bar);
;             __builtin_amdgcn_fence(__ATOMIC_ACQUIRE, "agent");
;             xb_add(&bar[XB_XGEN(b.x)], 1u);
;             asm volatile("s_waitcnt vmcnt(0)" ::: "memory");
;         } else {
;             XB_SPIN(xb_ld(&bar[XB_XGEN(b.x)]) == gen, bar);
.LBB0_2164:
	s_or_b64 exec, exec, s[6:7]
	v_cvt_f32_u32_e32 v4, v2
	s_waitcnt vmcnt(0)
	v_readfirstlane_b32 s4, v3
	v_sub_u32_e32 v3, 0, v2
	v_rcp_iflag_f32_e32 v4, v4
	v_add_u32_e32 v5, s4, v1
	v_mul_f32_e32 v4, 0x4f7ffffe, v4
	v_cvt_u32_f32_e32 v4, v4
	v_mul_lo_u32 v1, v3, v4
	v_mul_hi_u32 v1, v4, v1
	v_add_u32_e32 v1, v4, v1
	v_mul_hi_u32 v1, v5, v1
	v_mul_lo_u32 v3, v1, v2
	v_sub_u32_e32 v3, v5, v3
	v_add_u32_e32 v4, 1, v1
	v_cmp_ge_u32_e32 vcc, v3, v2
	s_nop 1
	v_cndmask_b32_e32 v1, v1, v4, vcc
	v_sub_u32_e32 v4, v3, v2
	v_cndmask_b32_e32 v3, v3, v4, vcc
	v_add_u32_e32 v4, 1, v1
	v_cmp_ge_u32_e32 vcc, v3, v2
	v_add_u32_e32 v3, 1, v5
	s_nop 0
	v_cndmask_b32_e32 v1, v1, v4, vcc
	v_mul_lo_u32 v4, v2, v1
	v_add_u32_e32 v2, v4, v2
	v_cmp_ne_u32_e32 vcc, v3, v2
	s_and_saveexec_b64 s[4:5], vcc
	s_xor_b64 s[4:5], exec, s[4:5]
	s_cbranch_execz .LBB0_2178
	s_waitcnt lgkmcnt(0)
	v_mov_b32_e32 v0, 0x7100
	global_load_dword v0, v0, s[30:31] offset:1024 sc1
	s_add_u32 s10, s30, 0x7500
	s_addc_u32 s11, s31, 0
	s_waitcnt vmcnt(0)
	v_cmp_eq_u32_e32 vcc, v0, v1
	s_and_saveexec_b64 s[6:7], vcc
	s_cbranch_execz .LBB0_2177
	s_add_u32 s8, s30, 0x4200
	s_addc_u32 s9, s31, 0
	s_mov_b32 s22, 1
	s_mov_b64 s[12:13], 0
	v_mov_b32_e32 v0, 0
	s_branch .LBB0_2168
